# scan loop software-pipelined by hand (LDS operand prefetch one step ahead, probe branches removed)
# speedup vs baseline: 1.0033x; 1.0033x over previous
.LBB0_1501:
	s_cmpk_gt_u32 s57, 0xbf
	s_cselect_b64 s[22:23], -1, 0
	s_and_b32 s8, s90, 56
	s_cmp_lg_u32 s8, 0
	s_cselect_b64 s[10:11], -1, 0
	s_bitcmp1_b32 s90, 6
	v_cndmask_b32_e64 v42, 0, 1, s[10:11]
	s_cselect_b64 s[24:25], -1, 0
	v_cmp_eq_u32_e64 s[8:9], 0, v50
	v_add_u32_e32 v160, v160, v158
	s_mov_b32 s35, 5
	s_movk_i32 s36, 0xfe
	v_cmp_ne_u32_e64 s[10:11], 1, v42
	s_movk_i32 s37, 0x1800
	v_add_u32_e32 v177, v157, v167
	ds_read_b128 v[134:137], v177
	v_add_u32_e32 v178, v157, v166
	ds_read_b128 v[138:141], v177 offset:4096
	ds_read_b128 v[126:129], v178
	v_add_u32_e32 v177, v157, v168
	ds_read_b128 v[130:133], v178 offset:4096
	ds_read_b128 v[118:121], v177
	v_add_u32_e32 v176, v157, v169
	ds_read_b128 v[122:125], v177 offset:4096
	ds_read_b128 v[114:117], v176
	ds_read_b128 v[110:113], v176 offset:4096
	s_and_b64 vcc, exec, s[12:13]
	s_cbranch_vccnz .Lsc_pre_noa
	ds_read_b128 v[2:5], v160 offset:24576
	ds_read_b128 v[6:9], v160 offset:25600
.Lsc_pre_noa:
	ds_read_b128 v[42:45], v159 offset:16384
	s_branch .LBB0_1504
.LBB0_1504:
	s_and_b64 vcc, exec, s[22:23]
	s_cbranch_vccz .Lsc_wlo
	s_waitcnt vmcnt(12)
	s_branch .Lsc_wdone
.Lsc_wlo:
	s_waitcnt vmcnt(14)
.Lsc_wdone:
	s_barrier
	s_andn2_b64 vcc, exec, s[16:17]
	s_mov_b64 s[26:27], -1
	s_cbranch_vccnz .LBB0_1521
	s_cmpk_lt_u32 s35, 0x104
	s_cselect_b32 s28, s36, 0
	s_mov_b64 s[26:27], 0

.LBB0_1523:
	s_add_i32 s29, s35, 4
	s_and_b32 s38, s29, 0xffff
	s_mul_i32 s38, s38, 0xcccd
	s_lshr_b32 s38, s38, 18
	s_mul_i32 s38, s38, 5
	s_sub_i32 s29, s29, s38
	s_and_b32 s29, s29, 0xffff
	s_add_i32 s26, s28, s31
	s_mulk_i32 s29, 0x6a00
	s_ashr_i32 s27, s26, 31
	s_add_i32 s38, s29, 0
	s_lshl_b64 s[40:41], s[26:27], 14
	s_add_i32 s29, s38, s30
	v_lshl_add_u64 v[180:181], v[142:143], 0, s[40:41]
	s_mov_b32 m0, s29
	s_and_b64 vcc, exec, s[0:1]
	global_load_lds_dwordx4 v[180:181], off
	v_lshl_add_u64 v[180:181], v[144:145], 0, s[40:41]
	s_add_i32 s40, s28, s34
	s_ashr_i32 s41, s40, 31
	s_add_i32 m0, s29, 0x2000
	s_lshl_b64 s[40:41], s[40:41], 15
	global_load_lds_dwordx4 v[180:181], off
	v_lshl_add_u64 v[180:181], v[146:147], 0, s[40:41]
	s_add_i32 m0, s29, 0x4000
	s_nop 0
	global_load_lds_dwordx4 v[180:181], off
	s_cbranch_vccnz .LBB0_1525
	s_lshl_b64 s[40:41], s[26:27], 11
	v_lshl_add_u64 v[180:181], v[148:149], 0, s[40:41]
	s_add_i32 m0, s29, 0x6000
	s_nop 0
	global_load_lds_dwordx4 v[180:181], off
.LBB0_1525:
	s_and_saveexec_b64 s[28:29], s[20:21]
	s_cbranch_execz .LBB0_1527
	s_lshl_b64 s[26:27], s[26:27], 10
	s_add_i32 m0, s38, 0x6800
	v_lshl_add_u64 v[180:181], v[150:151], 0, s[26:27]
	global_load_lds_dwordx4 v[180:181], off
.LBB0_1527:
	s_or_b64 exec, exec, s[28:29]
	s_waitcnt lgkmcnt(0)
	s_and_b32 s26, 0xffff, s35
	s_mul_i32 s26, s26, 0xcccd
	s_lshr_b32 s26, s26, 18
	s_mul_i32 s26, s26, 5
	s_sub_i32 s26, s35, s26
	s_and_b32 s26, s26, 0xffff
	s_mulk_i32 s26, 0x6a00
	v_add3_u32 v174, s26, v1, v158
	v_add_u32_e32 v175, s26, v156
	ds_read_b128 v[102:105], v174 offset:8192
	ds_read_b128 v[90:93], v174 offset:9216
	ds_read_b128 v[106:109], v175 offset:26624
	ds_read_b128 v[98:101], v175 offset:26688
	ds_read_b128 v[86:89], v174 offset:10240
	ds_read_b128 v[74:77], v174 offset:11264
	ds_read_b128 v[94:97], v175 offset:26752
	ds_read_b128 v[82:85], v175 offset:26816
	ds_read_b128 v[70:73], v174 offset:12288
	ds_read_b128 v[58:61], v174 offset:13312
	ds_read_b128 v[78:81], v175 offset:26880
	ds_read_b128 v[66:69], v175 offset:26944
	ds_read_b128 v[54:57], v174 offset:14336
	ds_read_b128 v[46:49], v174 offset:15360
	ds_read_b128 v[62:65], v175 offset:27008
	ds_read_b128 v[50:53], v175 offset:27072
	v_cvt_pk_bf16_f32 v170, v10, v11
	v_cvt_pk_bf16_f32 v171, v12, v13
	v_cvt_pk_bf16_f32 v172, v14, v15
	v_cvt_pk_bf16_f32 v173, v16, v17
	s_and_b64 vcc, exec, s[12:13]
	s_nop 0
	v_mfma_f32_16x16x32_bf16 v[134:137], v[170:173], v[134:137], 0
	v_mfma_f32_16x16x32_bf16 v[138:141], v[170:173], v[138:141], 0
	v_cvt_pk_bf16_f32 v170, v18, v19
	v_cvt_pk_bf16_f32 v171, v20, v21
	v_cvt_pk_bf16_f32 v172, v22, v23
	v_cvt_pk_bf16_f32 v173, v24, v25
	s_nop 0
	v_mfma_f32_16x16x32_bf16 v[126:129], v[170:173], v[126:129], v[134:137]
	v_cvt_pk_bf16_f32 v134, v26, v27
	v_cvt_pk_bf16_f32 v135, v28, v29
	v_cvt_pk_bf16_f32 v136, v30, v31
	v_mfma_f32_16x16x32_bf16 v[130:133], v[170:173], v[130:133], v[138:141]
	v_cvt_pk_bf16_f32 v137, v32, v33
	s_nop 3
	v_mfma_f32_16x16x32_bf16 v[118:121], v[134:137], v[118:121], v[126:129]
	v_cvt_pk_bf16_f32 v126, v34, v35
	v_cvt_pk_bf16_f32 v127, v36, v37
	v_cvt_pk_bf16_f32 v128, v38, v39
	v_mfma_f32_16x16x32_bf16 v[122:125], v[134:137], v[122:125], v[130:133]
	v_cvt_pk_bf16_f32 v129, v40, v41
	s_nop 0
	v_mfma_f32_16x16x32_bf16 v[114:117], v[126:129], v[114:117], v[118:121]
	v_mfma_f32_16x16x32_bf16 v[110:113], v[126:129], v[110:113], v[122:125]
	s_cbranch_vccnz .LBB0_1533
	v_mfma_f32_16x16x32_bf16 v[114:117], v[42:45], v[2:5], v[114:117]
	v_mfma_f32_16x16x32_bf16 v[110:113], v[42:45], v[6:9], v[110:113]
.LBB0_1533:
	s_add_i32 s28, s36, 4
	s_cmp_lt_u32 s35, 8
	s_cselect_b32 s26, 0x100, -8
	s_add_i32 s29, s26, s35
	s_and_b64 s[26:27], s[18:19], exec
	s_cselect_b32 s26, s29, s28
	s_lshl_b32 s26, s26, 5
	s_ashr_i32 s27, s26, 31
	v_lshl_add_u64 v[118:119], v[152:153], 0, s[26:27]
	v_mad_u64_u32 v[120:121], s[26:27], v118, s37, v[154:155]
	v_mov_b32_e32 v118, v121
	v_mad_u64_u32 v[118:119], s[26:27], v119, s37, v[118:119]
	v_mov_b32_e32 v121, v118
	v_cvt_pk_bf16_f32 v114, v114, v115
	v_cvt_pk_bf16_f32 v115, v116, v117
	global_store_dwordx2 v[120:121], v[114:115], off
	v_cvt_pk_bf16_f32 v110, v110, v111
	v_cvt_pk_bf16_f32 v111, v112, v113
	v_add_co_u32_e32 v112, vcc, 0x18000, v120
	s_nop 1
	v_addc_co_u32_e32 v113, vcc, 0, v118, vcc
	global_store_dwordx2 v[112:113], v[110:111], off
	s_waitcnt lgkmcnt(0)
	s_add_i32 s45, s35, 1
	s_and_b32 s46, 0xffff, s45
	s_mul_i32 s46, s46, 0xcccd
	s_lshr_b32 s46, s46, 18
	s_mul_i32 s46, s46, 5
	s_sub_i32 s45, s45, s46
	s_and_b32 s45, s45, 0xffff
	s_mulk_i32 s45, 0x6a00
	v_add_u32_e32 v176, s45, v157
	v_add_u32_e32 v177, v176, v167
	ds_read_b128 v[134:137], v177
	v_add_u32_e32 v178, v176, v166
	ds_read_b128 v[138:141], v177 offset:4096
	ds_read_b128 v[126:129], v178
	v_add_u32_e32 v177, v176, v168
	ds_read_b128 v[130:133], v178 offset:4096
	ds_read_b128 v[118:121], v177
	v_add_u32_e32 v176, v176, v169
	ds_read_b128 v[122:125], v177 offset:4096
	ds_read_b128 v[114:117], v176
	ds_read_b128 v[110:113], v176 offset:4096
	s_and_b64 vcc, exec, s[12:13]
	s_cbranch_vccnz .Lsc_noa
	v_add_u32_e32 v179, s45, v160
	ds_read_b128 v[2:5], v179 offset:24576
	ds_read_b128 v[6:9], v179 offset:25600
.Lsc_noa:
	v_pk_mul_f32 v[12:13], v[12:13], v[108:109]
	v_pk_mul_f32 v[10:11], v[10:11], v[106:107]
	v_pk_mul_f32 v[16:17], v[16:17], v[100:101]
	v_pk_mul_f32 v[14:15], v[14:15], v[98:99]
	v_pk_mul_f32 v[20:21], v[20:21], v[96:97]
	v_pk_mul_f32 v[18:19], v[18:19], v[94:95]
	v_pk_mul_f32 v[24:25], v[24:25], v[84:85]
	v_pk_mul_f32 v[22:23], v[22:23], v[82:83]
	v_pk_mul_f32 v[28:29], v[28:29], v[80:81]
	v_pk_mul_f32 v[26:27], v[26:27], v[78:79]
	v_pk_mul_f32 v[32:33], v[32:33], v[68:69]
	v_pk_mul_f32 v[30:31], v[30:31], v[66:67]
	v_pk_mul_f32 v[36:37], v[36:37], v[64:65]
	v_pk_mul_f32 v[34:35], v[34:35], v[62:63]
	v_pk_mul_f32 v[40:41], v[40:41], v[52:53]
	v_pk_mul_f32 v[38:39], v[38:39], v[50:51]
	v_mfma_f32_16x16x32_bf16 v[10:13], v[102:105], v[42:45], v[10:13]
	v_mfma_f32_16x16x32_bf16 v[14:17], v[90:93], v[42:45], v[14:17]
	v_mfma_f32_16x16x32_bf16 v[18:21], v[86:89], v[42:45], v[18:21]
	v_mfma_f32_16x16x32_bf16 v[22:25], v[74:77], v[42:45], v[22:25]
	v_mfma_f32_16x16x32_bf16 v[26:29], v[70:73], v[42:45], v[26:29]
	v_mfma_f32_16x16x32_bf16 v[30:33], v[58:61], v[42:45], v[30:33]
	v_mfma_f32_16x16x32_bf16 v[34:37], v[54:57], v[42:45], v[34:37]
	v_mfma_f32_16x16x32_bf16 v[38:41], v[46:49], v[42:45], v[38:41]
	v_add_u32_e32 v179, s45, v159
	ds_read_b128 v[42:45], v179 offset:16384
	s_add_i32 s35, s35, 1
	s_add_i32 s36, s36, -1
	s_cmp_lg_u32 s36, -5
	s_cbranch_scc1 .LBB0_1504
